# MLA PV block: two dead LDS-address adds per tile removed (their reads were hoisted earlier)
# speedup vs baseline: 1.0030x; 1.0030x over previous
; __device__ __forceinline__ unsigned pk2(float lo, float hi) { const f32x2 v = {lo, hi}; const bf16v2_t b = __builtin_convertvector(v, bf16v2_t); return __builtin_bit_cast(unsigned, b); }
; template <bool MLA>
; __device__ __forceinline__ void attn_phase(const Args& a, LAS unsigned char* lds) {
;     ...
;                 float mx = -INFINITY;
; #pragma unroll
;                 for (int sub = 0; sub < 4; ++sub) mx = fmaxf(fmaxf(fmaxf(mx, sv[sub][0]), fmaxf(sv[sub][1], sv[sub][2])), sv[sub][3]);
;                 mx = fmaxf(mx, __shfl_xor(mx, 16)); mx = fmaxf(mx, __shfl_xor(mx, 32));
;                 const float mn = fmaxf(m[g], mx), alpha = __builtin_amdgcn_exp2f(m[g] - mn); m[g] = mn;
;                 f32x4 ps4 = (f32x4){0.f, 0.f, 0.f, 0.f};
; #pragma unroll
;                 for (int sub = 0; sub < 4; ++sub) {
;                     const f32x4 d = sv[sub] - mn;
;                     const f32x4 pe = (f32x4){__builtin_amdgcn_exp2f(d[0]), __builtin_amdgcn_exp2f(d[1]), __builtin_amdgcn_exp2f(d[2]), __builtin_amdgcn_exp2f(d[3])};
;                     s[g][sub] = pe; ps4 += pe;
;                 }
;                 lsum[g] = lsum[g] * alpha + ((ps4[0] + ps4[1]) + (ps4[2] + ps4[3]));
; #pragma unroll
;                 for (int et = 0; et < 4; ++et) O[g][et] *= alpha;
; #pragma unroll
;                 for (int s2 = 0; s2 < 2; ++s2) {
;                     const unsigned a0 = pk2(s[g][2 * s2][0], s[g][2 * s2][1]), a1 = pk2(s[g][2 * s2][2], s[g][2 * s2][3]), a2 = pk2(s[g][2 * s2 + 1][0], s[g][2 * s2 + 1][1]), a3 = pk2(s[g][2 * s2 + 1][2], s[g][2 * s2 + 1][3]);
;                     const u32x4 pu = (u32x4){a0, a1, a2, a3}; pf[g][s2] = *(const bf16x8*)&pu;
;                 }
.LBB0_501:
	s_waitcnt lgkmcnt(0)
	v_max3_f32 v0, v175, v206, v207
	v_sub_f32_e32 v74, v155, v0
	v_sub_f32_e32 v75, v154, v0
	v_sub_f32_e32 v72, v153, v0
	v_sub_f32_e32 v73, v152, v0
	v_exp_f32_e32 v152, v75
	v_exp_f32_e32 v153, v74
	v_sub_f32_e32 v78, v148, v0
	v_sub_f32_e32 v79, v151, v0
	v_sub_f32_e32 v148, v150, v0
	v_sub_f32_e32 v77, v149, v0
	v_exp_f32_e32 v148, v148
	v_exp_f32_e32 v149, v79
	v_exp_f32_e32 v150, v78
	v_sub_f32_e32 v78, v144, v0
	v_sub_f32_e32 v79, v147, v0
	v_sub_f32_e32 v144, v146, v0
	v_sub_f32_e32 v76, v175, v0
	v_exp_f32_e32 v151, v77
	v_sub_f32_e32 v77, v145, v0
	v_exp_f32_e32 v144, v144
	v_exp_f32_e32 v145, v79
	v_exp_f32_e32 v146, v78
	v_sub_f32_e32 v78, v140, v0
	v_sub_f32_e32 v79, v143, v0
	v_sub_f32_e32 v140, v142, v0
	v_exp_f32_e32 v142, v140
	v_exp_f32_e32 v143, v79
	v_exp_f32_e32 v178, v76
	v_exp_f32_e32 v154, v73
	v_exp_f32_e32 v155, v72
	v_pk_add_f32 v[72:73], v[152:153], 0 op_sel_hi:[1,0]
	v_exp_f32_e32 v147, v77
	v_pk_add_f32 v[72:73], v[148:149], v[72:73]
	v_sub_f32_e32 v77, v141, v0
	v_pk_add_f32 v[72:73], v[144:145], v[72:73]
	v_exp_f32_e32 v176, v78
	v_pk_add_f32 v[72:73], v[142:143], v[72:73]
	v_pk_mul_f32 v[78:79], v[58:59], v[178:179] op_sel_hi:[1,0]
	v_pk_mul_f32 v[58:59], v[70:71], v[178:179] op_sel_hi:[1,0]
	v_cvt_pk_bf16_f32 v70, v142, v143
	v_max3_f32 v141, v136, v139, v138
	v_max3_f32 v142, v86, v81, v80
	v_max3_f32 v141, v141, v134, v85
	v_max3_f32 v142, v142, v2, v83
	v_max3_f32 v141, v141, v137, v84
	v_max3_f32 v142, v142, v87, v82
	s_mov_b32 s0, 0xff800000
	v_max_f32_e32 v141, v141, v135
	v_max3_f32 v141, v141, v142, v3
	ds_bpermute_b32 v142, v167, v141
	v_pk_add_f32 v[74:75], v[154:155], 0 op_sel_hi:[1,0]
	v_exp_f32_e32 v177, v77
	v_pk_add_f32 v[74:75], v[150:151], v[74:75]
	v_pk_mul_f32 v[76:77], v[56:57], v[178:179] op_sel_hi:[1,0]
	s_waitcnt lgkmcnt(0)
	v_max_f32_e32 v141, v141, v142
	ds_bpermute_b32 v142, v168, v141
	v_pk_add_f32 v[74:75], v[146:147], v[74:75]
	v_pk_mul_f32 v[56:57], v[68:69], v[178:179] op_sel_hi:[1,0]
	v_cvt_pk_bf16_f32 v69, v146, v147
	v_cvt_pk_bf16_f32 v68, v144, v145
	s_waitcnt lgkmcnt(0)
; #define LAS __attribute__((address_space(3)))
; template <bool MLA>
; __device__ __forceinline__ void attn_phase(const Args& a, LAS unsigned char* lds) {
;     ...
;                 float mx = -INFINITY;
; #pragma unroll
;                 for (int sub = 0; sub < 4; ++sub) mx = fmaxf(fmaxf(fmaxf(mx, sv[sub][0]), fmaxf(sv[sub][1], sv[sub][2])), sv[sub][3]);
;                 mx = fmaxf(mx, __shfl_xor(mx, 16)); mx = fmaxf(mx, __shfl_xor(mx, 32));
;                 const float mn = fmaxf(m[g], mx), alpha = __builtin_amdgcn_exp2f(m[g] - mn); m[g] = mn;
;                 f32x4 ps4 = (f32x4){0.f, 0.f, 0.f, 0.f};
; #pragma unroll
;                 for (int sub = 0; sub < 4; ++sub) {
;                     const f32x4 d = sv[sub] - mn;
;                     const f32x4 pe = (f32x4){__builtin_amdgcn_exp2f(d[0]), __builtin_amdgcn_exp2f(d[1]), __builtin_amdgcn_exp2f(d[2]), __builtin_amdgcn_exp2f(d[3])};
;                     s[g][sub] = pe; ps4 += pe;
;                 }
;                 lsum[g] = lsum[g] * alpha + ((ps4[0] + ps4[1]) + (ps4[2] + ps4[3]));
; #pragma unroll
;                 for (int et = 0; et < 4; ++et) O[g][et] *= alpha;
; #pragma unroll
;                 for (int s2 = 0; s2 < 2; ++s2) {
;                     const unsigned a0 = pk2(s[g][2 * s2][0], s[g][2 * s2][1]), a1 = pk2(s[g][2 * s2][2], s[g][2 * s2][3]), a2 = pk2(s[g][2 * s2 + 1][0], s[g][2 * s2 + 1][1]), a3 = pk2(s[g][2 * s2 + 1][2], s[g][2 * s2 + 1][3]);
;                     const u32x4 pu = (u32x4){a0, a1, a2, a3}; pf[g][s2] = *(const bf16x8*)&pu;
;                 }
;             }
; #pragma unroll
;             for (int s2 = 0; s2 < 2; ++s2)
; #pragma unroll
;                 for (int et = 0; et < 4; ++et) {
;                     const LAS bf16_t* vp = VTs + (et * 16 + r) * 68 + s2 * 32 + quad * 4;
;                     const u32x2 v0 = *(const LAS u32x2*)vp, v1 = *(const LAS u32x2*)(vp + 16);
;                     const u32x4 vu = (u32x4){v0.x, v0.y, v1.x, v1.y};
;                     O[0][et] = __builtin_amdgcn_mfma_f32_16x16x32_bf16(*(const bf16x8*)&vu, pf[0][s2], O[0][et], 0, 0, 0);
;                     O[1][et] = __builtin_amdgcn_mfma_f32_16x16x32_bf16(*(const bf16x8*)&vu, pf[1][s2], O[1][et], 0, 0, 0);
;                 }
	v_max3_f32 v141, v173, v141, v142
	v_add3_u32 v232, s68, v118, v169
	v_add_u32_e32 v233, 0x10000, v232
	v_add_u32_e32 v239, 0x10800, v232
	v_add_u32_e32 v240, 0x11000, v232
	v_add_u32_e32 v246, 0x11800, v232
	ds_read2_b64 v[208:211], v233 offset0:128 offset1:132
	ds_read2_b64 v[212:215], v239 offset0:144 offset1:148
	ds_read2_b64 v[216:219], v240 offset0:160 offset1:164
	ds_read2_b64 v[220:223], v246 offset0:176 offset1:180
	ds_read2_b64 v[224:227], v239 offset0:152 offset1:156
	ds_read2_b64 v[228:231], v240 offset0:168 offset1:172
	v_sub_f32_e32 v142, v137, v141
	v_sub_f32_e32 v143, v136, v141
	v_sub_f32_e32 v137, v139, v141
	v_sub_f32_e32 v136, v138, v141
	v_exp_f32_e32 v138, v143
	v_exp_f32_e32 v139, v142
	v_sub_f32_e32 v147, v135, v141
	v_sub_f32_e32 v146, v134, v141
	v_exp_f32_e32 v146, v146
	v_exp_f32_e32 v147, v147
	v_exp_f32_e32 v136, v136
	v_exp_f32_e32 v137, v137
	v_sub_f32_e32 v85, v85, v141
	v_sub_f32_e32 v84, v84, v141
	v_pk_add_f32 v[144:145], v[138:139], 0 op_sel_hi:[1,0]
	v_exp_f32_e32 v134, v84
	v_exp_f32_e32 v135, v85
	v_sub_f32_e32 v81, v81, v141
	v_sub_f32_e32 v80, v80, v141
	v_pk_add_f32 v[84:85], v[146:147], v[144:145]
	v_exp_f32_e32 v144, v80
	v_exp_f32_e32 v145, v81
	v_pk_add_f32 v[74:75], v[176:177], v[74:75]
	v_pk_add_f32 v[142:143], v[136:137], 0 op_sel_hi:[1,0]
	v_sub_f32_e32 v87, v87, v141
	v_sub_f32_e32 v86, v86, v141
	v_add_f32_e32 v72, v72, v73
	v_add_f32_e32 v73, v74, v75
	v_pk_mul_f32 v[74:75], v[62:63], v[178:179] op_sel_hi:[1,0]
	v_cvt_pk_bf16_f32 v62, v148, v149
	v_pk_add_f32 v[142:143], v[134:135], v[142:143]
	v_exp_f32_e32 v148, v86
	v_exp_f32_e32 v149, v87
	v_sub_f32_e32 v86, v3, v141
	v_sub_f32_e32 v87, v2, v141
	v_sub_f32_e32 v3, v83, v141
	v_sub_f32_e32 v2, v82, v141
	v_pk_add_f32 v[80:81], v[144:145], v[142:143]
	v_exp_f32_e32 v2, v2
	v_exp_f32_e32 v3, v3
	v_exp_f32_e32 v142, v87
	v_exp_f32_e32 v143, v86
	v_cvt_pk_bf16_f32 v63, v150, v151
	v_sub_f32_e32 v150, v173, v141
	v_pk_add_f32 v[84:85], v[148:149], v[84:85]
	v_pk_add_f32 v[80:81], v[2:3], v[80:81]
	v_pk_add_f32 v[82:83], v[142:143], v[84:85]
	v_exp_f32_e32 v150, v150
	v_pk_mov_b32 v[84:85], v[80:81], v[82:83] op_sel:[1,0]
	v_mov_b32_e32 v81, v83
	v_pk_add_f32 v[80:81], v[84:85], v[80:81]
	s_add_i32 s68, s68, 0xd000
	v_add_f32_e32 v151, v80, v81
	v_fmac_f32_e32 v151, v127, v150
	v_pk_mul_f32 v[82:83], v[42:43], v[150:151] op_sel_hi:[1,0]
	v_pk_mul_f32 v[42:43], v[54:55], v[150:151] op_sel_hi:[1,0]
	v_cvt_pk_bf16_f32 v54, v2, v3
	v_add3_u32 v2, s68, v118, v169
	v_add_u32_e32 v3, 0x3000, v2
	v_pk_mul_f32 v[86:87], v[46:47], v[150:151] op_sel_hi:[1,0]
	v_pk_mul_f32 v[84:85], v[44:45], v[150:151] op_sel_hi:[1,0]
	v_cvt_pk_bf16_f32 v44, v136, v137
	v_cvt_pk_bf16_f32 v46, v134, v135
	v_add_f32_e32 v140, v72, v73
	v_pk_mul_f32 v[72:73], v[60:61], v[178:179] op_sel_hi:[1,0]
	v_cvt_pk_bf16_f32 v60, v152, v153
	v_cvt_pk_bf16_f32 v61, v154, v155
	v_pk_mul_f32 v[80:81], v[40:41], v[150:151] op_sel_hi:[1,0]
	v_cvt_pk_bf16_f32 v45, v138, v139
	v_cvt_pk_bf16_f32 v47, v146, v147
	s_waitcnt lgkmcnt(0)
	v_mfma_f32_16x16x32_bf16 v[76:79], v[208:211], v[60:63], v[76:79]
	v_pk_mul_f32 v[66:67], v[66:67], v[178:179] op_sel_hi:[1,0]
	v_pk_mul_f32 v[64:65], v[64:65], v[178:179] op_sel_hi:[1,0]
	v_mfma_f32_16x16x32_bf16 v[80:83], v[208:211], v[44:47], v[80:83]
	v_pk_mul_f32 v[50:51], v[50:51], v[150:151] op_sel_hi:[1,0]
	v_pk_mul_f32 v[48:49], v[48:49], v[150:151] op_sel_hi:[1,0]
	v_mfma_f32_16x16x32_bf16 v[72:75], v[212:215], v[60:63], v[72:75]
	v_add_u32_e32 v2, 0x4800, v2
	v_pk_mul_f32 v[40:41], v[52:53], v[150:151] op_sel_hi:[1,0]
	v_cvt_pk_bf16_f32 v52, v144, v145
	v_mfma_f32_16x16x32_bf16 v[84:87], v[212:215], v[44:47], v[84:87]
	v_cvt_pk_bf16_f32 v55, v142, v143
	v_cvt_pk_bf16_f32 v71, v176, v177
	v_mfma_f32_16x16x32_bf16 v[64:67], v[216:219], v[60:63], v[64:67]
	v_cvt_pk_bf16_f32 v53, v148, v149
	v_fmac_f32_e32 v140, v174, v178
	v_mov_b32_e32 v173, v141
	v_mfma_f32_16x16x32_bf16 v[48:51], v[216:219], v[44:47], v[48:51]
	v_mov_b32_e32 v175, v0
	v_mov_b32_e32 v174, v140
	v_mfma_f32_16x16x32_bf16 v[142:145], v[220:223], v[60:63], v[56:59]
	s_movk_i32 s58, 0x420
	v_mfma_f32_16x16x32_bf16 v[134:137], v[220:223], v[44:47], v[40:43]
	v_mov_b32_e32 v127, v151
	v_mfma_f32_16x16x32_bf16 v[60:63], v[224:227], v[68:71], v[72:75]
	s_nop 2
	ds_read2_b64 v[40:43], v3 offset0:136 offset1:140
	ds_read2_b64 v[72:75], v2 offset0:184 offset1:188
	v_mfma_f32_16x16x32_bf16 v[64:67], v[228:231], v[68:71], v[64:67]
	v_mfma_f32_16x16x32_bf16 v[48:51], v[228:231], v[52:55], v[48:51]
	s_waitcnt lgkmcnt(1)
	v_mfma_f32_16x16x32_bf16 v[56:59], v[40:43], v[68:71], v[76:79]
	v_mfma_f32_16x16x32_bf16 v[40:43], v[40:43], v[52:55], v[80:83]
	v_mfma_f32_16x16x32_bf16 v[44:47], v[224:227], v[52:55], v[84:87]
	s_waitcnt lgkmcnt(0)
	v_mfma_f32_16x16x32_bf16 v[68:71], v[72:75], v[68:71], v[142:145]
	v_mfma_f32_16x16x32_bf16 v[52:55], v[72:75], v[52:55], v[134:137]
	s_add_i32 s66, s66, 64
	s_cmp_eq_u32 s63, s67
	s_cbranch_scc0 .LBB0_504
	s_branch .LBB0_505
